# band-attention sample units: duplicate waves get an empty tile range
# speedup vs baseline: 1.0057x; 1.0010x over previous
.LBB0_985:
	s_andn2_b64 vcc, exec, s[8:9]
	s_cbranch_vccnz .LBB0_987
	s_lshl_b32 s4, s15, 6
	s_or_b32 s40, s4, s76
	s_mul_i32 s15, s15, 0x120000
	s_add_u32 s4, s39, s15
	s_addc_u32 s5, s46, 0
	s_lshl_b32 s6, s14, 7
	s_lshl_b32 s8, s14, 8
	s_add_u32 s54, s4, s8
	s_addc_u32 s55, s5, 0
	s_add_u32 s4, s47, s15
	s_addc_u32 s5, s48, 0
	s_add_u32 s56, s4, s8
	s_mov_b32 s7, s41
	s_mov_b32 s13, 8
	s_addc_u32 s57, s5, 0
	s_mov_b32 s65, 10
	s_mov_b32 s11, 0
	s_mov_b32 s12, 0
	s_cmp_lg_u64 s[36:37], 0
	s_cselect_b32 s10, -1, 8
	s_mov_b32 s64, s49
	s_mov_b64 s[4:5], s[40:41]
